# mixer B: first two K/V tiles loaded together in the unit prologue; counted wait keeps the third tile in flight
# speedup vs baseline: 1.0111x; 1.0111x over previous
; #define LAS __attribute__((address_space(3)))
; #define GAS __attribute__((address_space(1)))
; __device__ __forceinline__ void b_unit(const bf16_t* Z, bf16_t* MIX, const float* sinks, ldsp lds, int b, int kvh, int qb, unsigned& gt, int wave0) {
;     int tid_; asm volatile("v_mbcnt_lo_u32_b32 %0, -1, 0\n\tv_mbcnt_hi_u32_b32 %0, -1, %0" : "=&v"(tid_)); tid_ += wave0 * 64; const int tid = tid_, lane = tid & 63, w = __builtin_amdgcn_readfirstlane(tid >> 6), r32 = lane & 31, hi = lane >> 5;
;     const int g = r32 >> 3, qq = r32 & 7, tq = 64 * qb + 8 * w + qq, head = kvh * 4 + g, key = tid >> 3, ch = tid & 7;
;     LAS float* wsf = (LAS float*)(lds + LDS_WSF) + w * 64;
;     const size_t tok = (size_t)b * T + tq;
;     bf16x8 qr[4]; q_load(qr, Z + tok * ZP0 + C_BQ + head * 64, hi);
;     float m = *(const GAS float*)(sinks + head) * LOG2E, l = (hi == 0) ? 1.f : 0.f;
;     f32x16 o[2], negm; splat16(negm, -m);
;     splat16(o[0], 0.f); splat16(o[1], 0.f);
;     const int n0 = qb >= 2 ? qb - 2 : 0;
;     const bf16_t* kvp = Z + ((size_t)b * T + key) * ZP0 + kvh * 64 + ch * 8;
;     u32x4 rk0 = ldg16(kvp + (size_t)(64 * n0) * ZP0 + C_BK), rv0 = ldg16(kvp + (size_t)(64 * n0) * ZP0 + C_BV), rk1 = rk0, rv1 = rv0;
;     if (n0 + 1 <= qb) { rk1 = ldg16(kvp + (size_t)(64 * (n0 + 1)) * ZP0 + C_BK); rv1 = ldg16(kvp + (size_t)(64 * (n0 + 1)) * ZP0 + C_BV); }
;     tile_store(lds + (gt & 1u) * 16384, rk0, rv0, key, ch);
;     if (n0 + 2 <= qb) { rk0 = ldg16(kvp + (size_t)(64 * (n0 + 2)) * ZP0 + C_BK); rv0 = ldg16(kvp + (size_t)(64 * (n0 + 2)) * ZP0 + C_BV); }
;     __syncthreads();
.LBB0_495:
	v_readlane_b32 s4, v254, 2
	v_readlane_b32 s5, v254, 3
	s_load_dwordx2 s[4:5], s[4:5], 0x60
	s_bfe_u32 s78, s2, 0x10006
	v_mbcnt_lo_u32_b32 v68, -1, 0
	v_mbcnt_hi_u32_b32 v68, -1, v68
	s_and_b32 s80, s2, 63
	v_bfe_u32 v16, v68, 3, 2
	v_lshl_or_b32 v50, s78, 2, v16
	v_lshlrev_b32_e32 v16, 2, v50
	s_waitcnt lgkmcnt(0)
	global_load_dword v56, v16, s[4:5]
	v_add_u32_e32 v48, s93, v68
	s_lshr_b32 s68, s2, 7
	v_readfirstlane_b32 s3, v48
	v_ashrrev_i32_e32 v64, 3, v48
	s_ashr_i32 s73, s3, 6
	s_lshl_b32 s79, s80, 6
	s_lshl_b64 s[70:71], s[68:69], 12
	v_ashrrev_i32_e32 v65, 31, v64
	s_lshl_b32 s72, s73, 3
	s_mov_b32 s4, 0x58000
	v_and_b32_e32 v69, 7, v68
	v_sub_u32_e64 v70, s80, 2 clamp
	v_lshlrev_b32_e32 v162, 7, v50
	v_lshl_add_u64 v[50:51], s[70:71], 0, v[64:65]
	s_add_i32 s6, s72, s79
	v_mul_lo_u32 v48, v70, s4
	v_mad_u64_u32 v[52:53], s[4:5], v50, s84, v[160:161]
	v_or_b32_e32 v166, s6, v69
	s_lshl_b32 s68, s78, 7
	v_mad_i32_i24 v53, v51, s84, v53
	v_ashrrev_i32_e32 v167, 31, v166
	v_lshl_add_u64 v[50:51], v[52:53], 0, s[68:69]
	v_lshl_add_u64 v[52:53], s[70:71], 0, v[166:167]
	v_mad_u64_u32 v[54:55], s[4:5], v52, s84, v[160:161]
	v_mad_i32_i24 v55, v53, s84, v55
	v_bfe_u32 v172, v68, 5, 1
	v_lshl_add_u64 v[52:53], v[54:55], 0, v[162:163]
	v_lshlrev_b32_e32 v162, 4, v69
	v_mov_b32_e32 v165, v163
	v_mov_b32_e32 v49, v163
	v_lshlrev_b32_e32 v164, 4, v172
	v_lshl_add_u64 v[168:169], v[50:51], 0, v[162:163]
	v_mov_b64_e32 v[30:31], v[14:15]
	v_mov_b64_e32 v[46:47], v[14:15]
	v_lshl_add_u64 v[52:53], v[52:53], 0, v[164:165]
	v_lshl_add_u64 v[66:67], v[168:169], 0, v[48:49]
	v_mov_b64_e32 v[28:29], v[12:13]
	v_mov_b64_e32 v[26:27], v[10:11]
	v_mov_b64_e32 v[24:25], v[8:9]
	v_mov_b64_e32 v[22:23], v[6:7]
	v_mov_b64_e32 v[20:21], v[4:5]
	v_mov_b64_e32 v[18:19], v[2:3]
	v_mov_b64_e32 v[16:17], v[0:1]
	v_mov_b64_e32 v[44:45], v[12:13]
	v_mov_b64_e32 v[42:43], v[10:11]
	v_mov_b64_e32 v[40:41], v[8:9]
	v_mov_b64_e32 v[38:39], v[6:7]
	v_mov_b64_e32 v[36:37], v[4:5]
	v_mov_b64_e32 v[34:35], v[2:3]
	v_mov_b64_e32 v[32:33], v[0:1]
	global_load_dwordx4 v[128:131], v[52:53], off offset:2560
	global_load_dwordx4 v[132:135], v[52:53], off offset:2592
	global_load_dwordx4 v[136:139], v[52:53], off offset:2624
	global_load_dwordx4 v[140:143], v[52:53], off offset:2656
	v_cmp_le_u32_e32 vcc, s80, v70
	v_readfirstlane_b32 s81, v70
	s_and_b64 vcc, exec, vcc
	s_waitcnt vmcnt(4)
	v_mul_f32_e32 v173, 0x3fb8aa3b, v56
	v_xor_b32_e32 v48, 0x80000000, v173
	v_mov_b32_e32 v49, v48
	v_mov_b32_e32 v50, v48
	v_mov_b32_e32 v51, v48
	v_mov_b32_e32 v52, v48
	v_mov_b32_e32 v53, v48
	v_mov_b32_e32 v54, v48
	v_mov_b32_e32 v55, v48
	v_mov_b32_e32 v56, v48
	v_mov_b32_e32 v57, v48
	v_mov_b32_e32 v58, v48
	v_mov_b32_e32 v59, v48
	v_mov_b32_e32 v60, v48
	v_mov_b32_e32 v61, v48
	v_mov_b32_e32 v62, v48
	v_mov_b32_e32 v63, v48
	global_load_dwordx4 v[144:147], v[66:67], off offset:3584
	global_load_dwordx4 v[148:151], v[66:67], off offset:3840
	s_cbranch_vccnz .Lb_pro_single
	v_add_co_u32_e32 v66, vcc, 0x58000, v66
	s_nop 1
	v_addc_co_u32_e32 v67, vcc, 0, v67, vcc
	global_load_dwordx4 v[152:155], v[66:67], off offset:3584
	global_load_dwordx4 v[156:159], v[66:67], off offset:3840
	s_waitcnt vmcnt(2)
	s_branch .LBB0_497
.Lb_pro_single:
	s_waitcnt vmcnt(0)
.LBB0_497:
	s_lshl_b32 s4, s82, 14
	s_and_b32 s4, s4, 0x4000
	v_lshlrev_b32_e32 v65, 5, v69
	v_lshlrev_b32_e32 v66, 4, v64
	s_add_i32 s4, s4, 0
	v_lshlrev_b32_e32 v175, 10, v69
	v_xor_b32_e32 v176, v66, v65
	v_lshlrev_b32_e32 v64, 6, v64
	v_add3_u32 v65, s4, v175, v176
	v_and_b32_e32 v177, 0x1000, v175
	v_and_b32_e32 v178, 0xfffffc00, v64
	ds_write_b128 v65, v[144:147]
	v_add3_u32 v65, s4, v177, v178
	v_and_b32_e32 v179, 0x3c0, v64
	v_and_b32_e32 v180, 48, v162
	s_add_i32 s4, s81, 2
	v_add3_u32 v64, v65, v179, v180
	s_cmp_gt_u32 s4, s80
	ds_write_b128 v64, v[148:151] offset:8192
	s_cbranch_scc1 .LBB0_499
	s_mul_i32 s68, s4, 0x58000
	v_lshl_add_u64 v[64:65], v[168:169], 0, s[68:69]
	global_load_dwordx4 v[144:147], v[64:65], off offset:3584
	global_load_dwordx4 v[148:151], v[64:65], off offset:3840

.LBB0_500:
	s_lshl_b32 s3, s82, 14
	s_and_b32 s3, s3, 0x4000
	s_cmp_lt_u32 s81, s80
	s_cselect_b64 s[40:41], -1, 0
	s_cmp_ge_u32 s81, s80
	s_cbranch_scc1 .LBB0_502
	s_xor_b32 s6, s3, 0x4000
	s_add_i32 s6, s6, 0
	v_add3_u32 v64, s6, v175, v176
	v_add3_u32 v65, s6, v177, v178
	v_add3_u32 v65, v65, v179, v180
	s_add_i32 s6, s81, 2
	s_cmp_le_u32 s6, s80
	s_cbranch_scc1 .Lb_deep_a
	s_waitcnt vmcnt(1)
	ds_write_b128 v64, v[152:155]
	s_waitcnt vmcnt(0)
	ds_write_b128 v65, v[156:159] offset:8192
	s_branch .LBB0_502
.Lb_deep_a:
	s_waitcnt vmcnt(3)
	ds_write_b128 v64, v[152:155]
	s_waitcnt vmcnt(2)
	ds_write_b128 v65, v[156:159] offset:8192
